# PEER gather: per-token expert list bucket-sorted by table region (8 x 4MiB), alternating sweep direction per token, for L2 reuse across the waves of an XCD; summation order of the expert sum changes (
# speedup vs baseline: 1.0681x; 1.0340x over previous
.LBB0_869:
	ds_read2st64_b32 v[4:5], v220 offset0:12 offset1:13
	ds_read2st64_b32 v[6:7], v220 offset0:14 offset1:15
	v_mov_b32_e32 v10, 0
	v_mov_b32_e32 v11, 0
	s_mov_b32 s0, 0
	s_waitcnt lgkmcnt(0)
	v_lshrrev_b32_e32 v8, 11, v4
	v_lshrrev_b32_e32 v9, 11, v5
	v_cmp_eq_u32_e64 s[42:43], 0, v8
	v_cmp_eq_u32_e64 s[100:101], 0, v9
	s_bcnt1_i32_b64 s1, s[42:43]
	s_bcnt1_i32_b64 s41, s[100:101]
	v_mbcnt_lo_u32_b32 v12, s42, 0
	v_mbcnt_hi_u32_b32 v12, s43, v12
	v_mbcnt_lo_u32_b32 v13, s100, 0
	v_mbcnt_hi_u32_b32 v13, s101, v13
	s_add_i32 s98, s0, s1
	v_add_u32_e32 v12, s0, v12
	v_add_u32_e32 v13, s98, v13
	v_cndmask_b32_e64 v10, v10, v12, s[42:43]
	v_cndmask_b32_e64 v11, v11, v13, s[100:101]
	s_add_i32 s0, s98, s41
	v_cmp_eq_u32_e64 s[42:43], 1, v8
	v_cmp_eq_u32_e64 s[100:101], 1, v9
	s_bcnt1_i32_b64 s1, s[42:43]
	s_bcnt1_i32_b64 s41, s[100:101]
	v_mbcnt_lo_u32_b32 v12, s42, 0
	v_mbcnt_hi_u32_b32 v12, s43, v12
	v_mbcnt_lo_u32_b32 v13, s100, 0
	v_mbcnt_hi_u32_b32 v13, s101, v13
	s_add_i32 s98, s0, s1
	v_add_u32_e32 v12, s0, v12
	v_add_u32_e32 v13, s98, v13
	v_cndmask_b32_e64 v10, v10, v12, s[42:43]
	v_cndmask_b32_e64 v11, v11, v13, s[100:101]
	s_add_i32 s0, s98, s41
	v_cmp_eq_u32_e64 s[42:43], 2, v8
	v_cmp_eq_u32_e64 s[100:101], 2, v9
	s_bcnt1_i32_b64 s1, s[42:43]
	s_bcnt1_i32_b64 s41, s[100:101]
	v_mbcnt_lo_u32_b32 v12, s42, 0
	v_mbcnt_hi_u32_b32 v12, s43, v12
	v_mbcnt_lo_u32_b32 v13, s100, 0
	v_mbcnt_hi_u32_b32 v13, s101, v13
	s_add_i32 s98, s0, s1
	v_add_u32_e32 v12, s0, v12
	v_add_u32_e32 v13, s98, v13
	v_cndmask_b32_e64 v10, v10, v12, s[42:43]
	v_cndmask_b32_e64 v11, v11, v13, s[100:101]
	s_add_i32 s0, s98, s41
	v_cmp_eq_u32_e64 s[42:43], 3, v8
	v_cmp_eq_u32_e64 s[100:101], 3, v9
	s_bcnt1_i32_b64 s1, s[42:43]
	s_bcnt1_i32_b64 s41, s[100:101]
	v_mbcnt_lo_u32_b32 v12, s42, 0
	v_mbcnt_hi_u32_b32 v12, s43, v12
	v_mbcnt_lo_u32_b32 v13, s100, 0
	v_mbcnt_hi_u32_b32 v13, s101, v13
	s_add_i32 s98, s0, s1
	v_add_u32_e32 v12, s0, v12
	v_add_u32_e32 v13, s98, v13
	v_cndmask_b32_e64 v10, v10, v12, s[42:43]
	v_cndmask_b32_e64 v11, v11, v13, s[100:101]
	s_add_i32 s0, s98, s41
	v_cmp_eq_u32_e64 s[42:43], 4, v8
	v_cmp_eq_u32_e64 s[100:101], 4, v9
	s_bcnt1_i32_b64 s1, s[42:43]
	s_bcnt1_i32_b64 s41, s[100:101]
	v_mbcnt_lo_u32_b32 v12, s42, 0
	v_mbcnt_hi_u32_b32 v12, s43, v12
	v_mbcnt_lo_u32_b32 v13, s100, 0
	v_mbcnt_hi_u32_b32 v13, s101, v13
	s_add_i32 s98, s0, s1
	v_add_u32_e32 v12, s0, v12
	v_add_u32_e32 v13, s98, v13
	v_cndmask_b32_e64 v10, v10, v12, s[42:43]
	v_cndmask_b32_e64 v11, v11, v13, s[100:101]
	s_add_i32 s0, s98, s41
	v_cmp_eq_u32_e64 s[42:43], 5, v8
	v_cmp_eq_u32_e64 s[100:101], 5, v9
	s_bcnt1_i32_b64 s1, s[42:43]
	s_bcnt1_i32_b64 s41, s[100:101]
	v_mbcnt_lo_u32_b32 v12, s42, 0
	v_mbcnt_hi_u32_b32 v12, s43, v12
	v_mbcnt_lo_u32_b32 v13, s100, 0
	v_mbcnt_hi_u32_b32 v13, s101, v13
	s_add_i32 s98, s0, s1
	v_add_u32_e32 v12, s0, v12
	v_add_u32_e32 v13, s98, v13
	v_cndmask_b32_e64 v10, v10, v12, s[42:43]
	v_cndmask_b32_e64 v11, v11, v13, s[100:101]
	s_add_i32 s0, s98, s41
	v_cmp_eq_u32_e64 s[42:43], 6, v8
	v_cmp_eq_u32_e64 s[100:101], 6, v9
	s_bcnt1_i32_b64 s1, s[42:43]
	s_bcnt1_i32_b64 s41, s[100:101]
	v_mbcnt_lo_u32_b32 v12, s42, 0
	v_mbcnt_hi_u32_b32 v12, s43, v12
	v_mbcnt_lo_u32_b32 v13, s100, 0
	v_mbcnt_hi_u32_b32 v13, s101, v13
	s_add_i32 s98, s0, s1
	v_add_u32_e32 v12, s0, v12
	v_add_u32_e32 v13, s98, v13
	v_cndmask_b32_e64 v10, v10, v12, s[42:43]
	v_cndmask_b32_e64 v11, v11, v13, s[100:101]
	s_add_i32 s0, s98, s41
	v_cmp_eq_u32_e64 s[42:43], 7, v8
	v_cmp_eq_u32_e64 s[100:101], 7, v9
	s_bcnt1_i32_b64 s1, s[42:43]
	s_bcnt1_i32_b64 s41, s[100:101]
	v_mbcnt_lo_u32_b32 v12, s42, 0
	v_mbcnt_hi_u32_b32 v12, s43, v12
	v_mbcnt_lo_u32_b32 v13, s100, 0
	v_mbcnt_hi_u32_b32 v13, s101, v13
	s_add_i32 s98, s0, s1
	v_add_u32_e32 v12, s0, v12
	v_add_u32_e32 v13, s98, v13
	v_cndmask_b32_e64 v10, v10, v12, s[42:43]
	v_cndmask_b32_e64 v11, v11, v13, s[100:101]
	s_add_i32 s0, s98, s41
	s_and_b32 s1, s19, 1
	s_mul_i32 s1, s1, 0x7f
	v_xor_b32_e32 v10, s1, v10
	v_xor_b32_e32 v11, s1, v11
	v_lshl_add_u32 v10, v10, 2, v199
	v_lshl_add_u32 v11, v11, 2, v199
	ds_write_b32 v10, v4
	ds_write_b32 v11, v5
	ds_write_b32 v10, v6 offset:512
	ds_write_b32 v11, v7 offset:512
	v_add_u32_e32 v0, s48, v0
	v_cmp_gt_i32_e32 vcc, s52, v0
	v_mov_b32_e32 v2, s49
	v_mov_b32_e32 v3, s50
	v_cndmask_b32_e32 v2, v2, v3, vcc
	v_add_u32_e32 v152, v0, v2
	v_ashrrev_i32_e32 v153, 31, v152
	v_lshlrev_b64 v[2:3], 11, v[152:153]
	v_lshl_add_u64 v[2:3], v[138:139], 0, v[2:3]
	global_load_dwordx2 v[4:5], v[2:3], off
	s_lshl_b32 s0, s19, 10
	s_waitcnt lgkmcnt(0)
	v_add3_u32 v9, v131, s0, v136
	v_mov_b32_e32 v184, 0
	s_mov_b32 s1, 0
	v_mov_b32_e32 v185, v184
	v_mov_b32_e32 v186, v184
	v_mov_b32_e32 v187, v184
	v_mov_b32_e32 v182, v184
	v_mov_b32_e32 v183, v184
	v_mov_b32_e32 v180, v184
	v_mov_b32_e32 v181, v184
	v_mov_b32_e32 v178, v184
	v_mov_b32_e32 v179, v184
	v_mov_b32_e32 v176, v184
	v_mov_b32_e32 v177, v184
	v_mov_b32_e32 v174, v184
	v_mov_b32_e32 v175, v184
	v_mov_b32_e32 v172, v184
	v_mov_b32_e32 v173, v184
	s_waitcnt vmcnt(0)
	v_lshlrev_b32_e32 v154, 16, v4
	v_and_b32_e32 v155, 0xffff0000, v4
	v_lshlrev_b32_e32 v156, 16, v5
	v_and_b32_e32 v157, 0xffff0000, v5
	global_load_dwordx2 v[4:5], v[2:3], off offset:512
	s_waitcnt vmcnt(0)
	v_lshlrev_b32_e32 v158, 16, v4
	v_and_b32_e32 v159, 0xffff0000, v4
	v_lshlrev_b32_e32 v162, 16, v5
	v_and_b32_e32 v163, 0xffff0000, v5
	global_load_dwordx2 v[4:5], v[2:3], off offset:1024
	s_waitcnt vmcnt(0)
	v_lshlrev_b32_e32 v164, 16, v4
	global_load_dwordx2 v[2:3], v[2:3], off offset:1536
	v_and_b32_e32 v165, 0xffff0000, v4
	v_lshlrev_b32_e32 v166, 16, v5
	v_and_b32_e32 v167, 0xffff0000, v5
	s_waitcnt vmcnt(0)
	v_lshlrev_b32_e32 v168, 16, v2
	v_and_b32_e32 v169, 0xffff0000, v2
	v_lshlrev_b32_e32 v170, 16, v3
	v_and_b32_e32 v171, 0xffff0000, v3
	ds_read2st64_b32 v[2:3], v220 offset0:12 offset1:13
	s_waitcnt lgkmcnt(0)
	v_mov_b32_e32 v0, v2
	v_lshlrev_b64 v[4:5], 2, v[0:1]
	v_lshl_add_u64 v[6:7], s[34:35], 0, v[4:5]
	v_lshl_add_u64 v[4:5], s[90:91], 0, v[4:5]
	global_load_dword v8, v[6:7], off
	global_load_dword v0, v[4:5], off
	ds_read2st64_b32 v[6:7], v220 offset0:14 offset1:15
	s_waitcnt vmcnt(0) lgkmcnt(0)
	v_mul_f32_e32 v6, v6, v0
	v_mov_b32_e32 v0, v3
	v_lshlrev_b64 v[2:3], 2, v[0:1]
	v_lshl_add_u64 v[4:5], s[34:35], 0, v[2:3]
	global_load_dword v0, v[4:5], off
	v_lshl_add_u64 v[2:3], s[90:91], 0, v[2:3]
	s_waitcnt vmcnt(0)
	ds_write2st64_b32 v9, v8, v0 offset1:1
	global_load_dword v0, v[2:3], off
	s_waitcnt vmcnt(0)
	v_mul_f32_e32 v0, v7, v0
	ds_write2st64_b32 v9, v6, v0 offset0:2 offset1:3
